# prologue x -> XB/SS conversion: two prompt rows per trip, all 8 loads in flight, interleaved cross-lane reductions
# speedup vs baseline: 1.0298x; 1.0015x over previous
; __device__ __forceinline__ unsigned cvt_pk_bf16(float lo, float hi) { unsigned r; asm("v_cvt_pk_bf16_f32 %0, %1, %2" : "=v"(r) : "v"(lo), "v"(hi)); return r; }
; __device__ __forceinline__ void prologue(const Params& P, LAS unsigned char* lds, int G, int vcu) {
;     ...
;     for (int m = gw; m < T + 512; m += NGW) {
;         const bool ismem = m >= T;
;         const float* xp0 = P.in[0]; const float* xs0 = P.in[1]; const float* mp0 = P.in[2];
;         const float* src = ismem ? mp0 + (size_t)(m - T) * D : (m < TP ? xp0 + (size_t)m * D : xs0 + (size_t)(m - TP) * D);
;         f32x4 v[4]; float ss = 0.f;
; #pragma unroll
;         for (int j = 0; j < 4; ++j) { v[j] = ((const f32x4*)src)[lane + 64 * j]; ss += (v[j][0] * v[j][0] + v[j][1] * v[j][1]) + (v[j][2] * v[j][2] + v[j][3] * v[j][3]); }
;         ss = wave_sum(ss);
;         bf16_t* xb = ismem ? (bf16_t*)(ws + WS_MEMB) + (size_t)(m - T) * D : XB + (size_t)m * D;
;         float* ssp = ismem ? (float*)(ws + WS_SSM) + (size_t)(m - T) * 16 : SS + (size_t)m * 16;
; #pragma unroll
;         for (int j = 0; j < 4; ++j) {
;             u32x2 w; w.x = cvt_pk_bf16(v[j][0], v[j][1]); w.y = cvt_pk_bf16(v[j][2], v[j][3]);
;             ((u32x2*)xb)[lane + 64 * j] = w;
;         }
;         if (lane < 16) ssp[lane] = lane == 0 ? ss : 0.f;
;     }
.LBB0_201:
	s_add_i32 s10, s8, s60
	s_cmpk_lt_i32 s10, 0x4000
	s_cbranch_scc0 .Lxc_slow
	v_readlane_b32 s36, v253, 55
	v_readlane_b32 s37, v253, 56
	s_ashr_i32 s11, s10, 31
	s_lshl_b64 s[16:17], s[8:9], 12
	s_lshl_b64 s[18:19], s[10:11], 12
	s_add_u32 s16, s36, s16
	s_addc_u32 s17, s37, s17
	s_add_u32 s18, s36, s18
	s_addc_u32 s19, s37, s19
	global_load_dwordx4 v[12:15], v7, s[16:17]
	global_load_dwordx4 v[16:19], v7, s[16:17] offset:1024
	global_load_dwordx4 v[20:23], v7, s[16:17] offset:2048
	global_load_dwordx4 v[24:27], v7, s[16:17] offset:3072
	global_load_dwordx4 v[40:43], v7, s[18:19]
	global_load_dwordx4 v[44:47], v7, s[18:19] offset:1024
	global_load_dwordx4 v[48:51], v7, s[18:19] offset:2048
	global_load_dwordx4 v[52:55], v7, s[18:19] offset:3072
	s_lshl_b64 s[12:13], s[8:9], 11
	s_add_u32 s12, s12, 0x4200000
	s_addc_u32 s13, s13, 0
	s_add_u32 s12, s12, s94
	s_addc_u32 s13, s13, s95
	s_lshl_b64 s[14:15], s[10:11], 11
	s_add_u32 s14, s14, 0x4200000
	s_addc_u32 s15, s15, 0
	s_add_u32 s14, s14, s94
	s_addc_u32 s15, s15, s95
	s_lshl_b64 s[38:39], s[8:9], 6
	s_add_u32 s38, s38, 0x6300000
	s_addc_u32 s39, s39, 0
	s_add_u32 s38, s38, s94
	s_addc_u32 s39, s39, s95
	s_lshl_b64 s[40:41], s[10:11], 6
	s_add_u32 s40, s40, 0x6300000
	s_addc_u32 s41, s41, 0
	s_add_u32 s40, s40, s94
	s_addc_u32 s41, s41, s95
	s_waitcnt vmcnt(7)
	v_mul_f32_e32 v11, v13, v13
	v_mul_f32_e32 v28, v15, v15
	s_waitcnt vmcnt(6)
	v_mul_f32_e32 v29, v17, v17
	v_mul_f32_e32 v30, v19, v19
	s_waitcnt vmcnt(5)
	v_mul_f32_e32 v31, v21, v21
	v_mul_f32_e32 v32, v23, v23
	v_fmac_f32_e32 v11, v12, v12
	v_fmac_f32_e32 v28, v14, v14
	v_fmac_f32_e32 v29, v16, v16
	v_fmac_f32_e32 v30, v18, v18
	s_waitcnt vmcnt(4)
	v_mul_f32_e32 v33, v25, v25
	v_mul_f32_e32 v35, v27, v27
	v_fmac_f32_e32 v31, v20, v20
	v_fmac_f32_e32 v32, v22, v22
	v_add_f32_e32 v11, v11, v28
	v_add_f32_e32 v28, v29, v30
	v_fmac_f32_e32 v33, v24, v24
	v_fmac_f32_e32 v35, v26, v26
	v_add_f32_e32 v29, v31, v32
	v_add_f32_e32 v11, v11, v28
	v_add_f32_e32 v30, v33, v35
	v_add_f32_e32 v11, v11, v29
	v_add_f32_e32 v11, v11, v30
	ds_bpermute_b32 v28, v1, v11
	v_cvt_pk_bf16_f32 v12, v12, v13
	v_cvt_pk_bf16_f32 v13, v14, v15
	v_cvt_pk_bf16_f32 v14, v16, v17
	v_cvt_pk_bf16_f32 v15, v18, v19
	v_cvt_pk_bf16_f32 v16, v20, v21
	v_cvt_pk_bf16_f32 v17, v22, v23
	v_cvt_pk_bf16_f32 v18, v24, v25
	v_cvt_pk_bf16_f32 v19, v26, v27
	global_store_dwordx2 v8, v[12:13], s[12:13]
	global_store_dwordx2 v8, v[14:15], s[12:13] offset:512
	global_store_dwordx2 v8, v[16:17], s[12:13] offset:1024
	global_store_dwordx2 v8, v[18:19], s[12:13] offset:1536
	s_waitcnt vmcnt(7)
	v_mul_f32_e32 v56, v41, v41
	v_mul_f32_e32 v57, v43, v43
	s_waitcnt vmcnt(6)
	v_mul_f32_e32 v58, v45, v45
	v_mul_f32_e32 v59, v47, v47
	s_waitcnt vmcnt(5)
	v_mul_f32_e32 v60, v49, v49
	v_mul_f32_e32 v61, v51, v51
	v_fmac_f32_e32 v56, v40, v40
	v_fmac_f32_e32 v57, v42, v42
	v_fmac_f32_e32 v58, v44, v44
	v_fmac_f32_e32 v59, v46, v46
	s_waitcnt vmcnt(4)
	v_mul_f32_e32 v62, v53, v53
	v_mul_f32_e32 v63, v55, v55
	v_fmac_f32_e32 v60, v48, v48
	v_fmac_f32_e32 v61, v50, v50
	v_add_f32_e32 v56, v56, v57
	v_add_f32_e32 v57, v58, v59
	v_fmac_f32_e32 v62, v52, v52
	v_fmac_f32_e32 v63, v54, v54
	v_add_f32_e32 v58, v60, v61
	v_add_f32_e32 v56, v56, v57
	v_add_f32_e32 v59, v62, v63
	v_add_f32_e32 v56, v56, v58
	v_add_f32_e32 v56, v56, v59
	ds_bpermute_b32 v57, v1, v56
	v_cvt_pk_bf16_f32 v40, v40, v41
	v_cvt_pk_bf16_f32 v41, v42, v43
	v_cvt_pk_bf16_f32 v42, v44, v45
	v_cvt_pk_bf16_f32 v43, v46, v47
	v_cvt_pk_bf16_f32 v44, v48, v49
	v_cvt_pk_bf16_f32 v45, v50, v51
	v_cvt_pk_bf16_f32 v46, v52, v53
	v_cvt_pk_bf16_f32 v47, v54, v55
	global_store_dwordx2 v8, v[40:41], s[14:15]
	global_store_dwordx2 v8, v[42:43], s[14:15] offset:512
	global_store_dwordx2 v8, v[44:45], s[14:15] offset:1024
	global_store_dwordx2 v8, v[46:47], s[14:15] offset:1536
	s_waitcnt lgkmcnt(1)
	v_add_f32_e32 v11, v11, v28
	ds_bpermute_b32 v28, v2, v11
	s_waitcnt lgkmcnt(1)
	v_add_f32_e32 v56, v56, v57
	ds_bpermute_b32 v57, v2, v56
	s_waitcnt lgkmcnt(1)
	v_add_f32_e32 v11, v11, v28
	ds_bpermute_b32 v28, v3, v11
	s_waitcnt lgkmcnt(1)
	v_add_f32_e32 v56, v56, v57
	ds_bpermute_b32 v57, v3, v56
	s_waitcnt lgkmcnt(1)
	v_add_f32_e32 v11, v11, v28
	ds_bpermute_b32 v28, v4, v11
	s_waitcnt lgkmcnt(1)
	v_add_f32_e32 v56, v56, v57
	ds_bpermute_b32 v57, v4, v56
	s_waitcnt lgkmcnt(1)
	v_add_f32_e32 v11, v11, v28
	ds_bpermute_b32 v28, v5, v11
	s_waitcnt lgkmcnt(1)
	v_add_f32_e32 v56, v56, v57
	ds_bpermute_b32 v57, v5, v56
	s_waitcnt lgkmcnt(1)
	v_add_f32_e32 v11, v11, v28
	ds_bpermute_b32 v28, v6, v11
	s_waitcnt lgkmcnt(1)
	v_add_f32_e32 v56, v56, v57
	ds_bpermute_b32 v57, v6, v56
	s_waitcnt lgkmcnt(1)
	v_add_f32_e32 v11, v11, v28
	s_waitcnt lgkmcnt(0)
	v_add_f32_e32 v56, v56, v57
	s_and_saveexec_b64 s[42:43], s[0:1]
	v_cndmask_b32_e64 v11, 0, v11, s[2:3]
	v_cndmask_b32_e64 v56, 0, v56, s[2:3]
	global_store_dword v9, v11, s[38:39]
	global_store_dword v9, v56, s[40:41]
	s_or_b64 exec, exec, s[42:43]
	s_add_u32 s8, s8, s60
	s_addc_u32 s9, s9, s20
	s_mov_b64 s[14:15], exec
	s_branch .LBB0_200
